# v58 + GEMM unit headers: the 128 accumulator-zeroing v_mov_b32 replaced by 64 v_mov_b64
# speedup vs baseline: 1.0100x; 1.0029x over previous
.LBB0_219:
	s_ashr_i32 s45, s44, 31
	s_lshl_b64 s[46:47], s[44:45], 19
	s_add_u32 s46, s14, s46
	s_addc_u32 s47, s15, s47
	s_and_b64 s[48:49], s[6:7], exec
	s_cselect_b32 s9, s47, s51
	s_cselect_b32 s11, s46, s50
	s_ashr_i32 s43, s42, 31
	s_lshl_b64 s[48:49], s[42:43], 19
	s_add_u32 s48, s27, s48
	s_addc_u32 s49, s29, s49
	s_and_b64 s[54:55], s[6:7], exec
	s_cselect_b32 s20, s49, s53
	s_cselect_b32 s33, s48, s52
	s_add_u32 s50, s50, 0x40080
	s_addc_u32 s51, s51, 0
	s_add_u32 s43, s52, 0x100
	s_addc_u32 s45, s53, 0
	s_mov_b32 s66, -2
	v_mov_b64_e32 v[0:1], 0
	s_waitcnt lgkmcnt(0)
	v_mov_b64_e32 v[2:3], 0
	v_mov_b64_e32 v[4:5], 0
	v_mov_b64_e32 v[6:7], 0
	v_mov_b64_e32 v[16:17], 0
	v_mov_b64_e32 v[18:19], 0
	v_mov_b64_e32 v[20:21], 0
	v_mov_b64_e32 v[22:23], 0
	v_mov_b64_e32 v[32:33], 0
	v_mov_b64_e32 v[34:35], 0
	v_mov_b64_e32 v[36:37], 0
	v_mov_b64_e32 v[38:39], 0
	s_waitcnt vmcnt(0)
	v_mov_b64_e32 v[48:49], 0
	v_mov_b64_e32 v[50:51], 0
	v_mov_b64_e32 v[52:53], 0
	v_mov_b64_e32 v[54:55], 0
	v_mov_b64_e32 v[8:9], 0
	v_mov_b64_e32 v[10:11], 0
	v_mov_b64_e32 v[12:13], 0
	v_mov_b64_e32 v[14:15], 0
	v_mov_b64_e32 v[24:25], 0
	v_mov_b64_e32 v[26:27], 0
	v_mov_b64_e32 v[28:29], 0
	v_mov_b64_e32 v[30:31], 0
	v_mov_b64_e32 v[40:41], 0
	v_mov_b64_e32 v[42:43], 0
	v_mov_b64_e32 v[44:45], 0
	v_mov_b64_e32 v[46:47], 0
	v_mov_b64_e32 v[56:57], 0
	v_mov_b64_e32 v[58:59], 0
	v_mov_b64_e32 v[60:61], 0
	v_mov_b64_e32 v[62:63], 0
	v_mov_b64_e32 v[64:65], 0
	v_mov_b64_e32 v[66:67], 0
	v_mov_b64_e32 v[68:69], 0
	v_mov_b64_e32 v[70:71], 0
	v_mov_b64_e32 v[80:81], 0
	v_mov_b64_e32 v[82:83], 0
	v_mov_b64_e32 v[84:85], 0
	v_mov_b64_e32 v[86:87], 0
	v_mov_b64_e32 v[96:97], 0
	v_mov_b64_e32 v[98:99], 0
	v_mov_b64_e32 v[100:101], 0
	v_mov_b64_e32 v[102:103], 0
	v_mov_b64_e32 v[112:113], 0
	v_mov_b64_e32 v[114:115], 0
	v_mov_b64_e32 v[116:117], 0
	v_mov_b64_e32 v[118:119], 0
	v_mov_b64_e32 v[72:73], 0
	v_mov_b64_e32 v[74:75], 0
	v_mov_b64_e32 v[76:77], 0
	v_mov_b64_e32 v[78:79], 0
	v_mov_b64_e32 v[88:89], 0
	v_mov_b64_e32 v[90:91], 0
	v_mov_b64_e32 v[92:93], 0
	v_mov_b64_e32 v[94:95], 0
	v_mov_b64_e32 v[104:105], 0
	v_mov_b64_e32 v[106:107], 0
	v_mov_b64_e32 v[108:109], 0
	v_mov_b64_e32 v[110:111], 0
	v_mov_b64_e32 v[120:121], 0
	v_mov_b64_e32 v[122:123], 0
	v_mov_b64_e32 v[124:125], 0
	v_mov_b64_e32 v[126:127], 0
	s_cmp_lg_u32 s90, 0
	s_cbranch_scc0 .Lkl_nobar_0
	s_barrier
	s_mov_b32 s90, 0

.LBB0_400:
	s_ashr_i32 s35, s34, 31
	s_lshl_b64 s[36:37], s[34:35], 20
	s_add_u32 s36, s14, s36
	s_addc_u32 s37, s15, s37
	s_and_b64 s[38:39], s[8:9], exec
	s_cselect_b32 s35, s37, s43
	s_cselect_b32 s41, s36, s42
	s_ashr_i32 s31, s30, 31
	s_lshl_b64 s[38:39], s[30:31], 20
	s_add_u32 s38, s20, s38
	s_addc_u32 s39, s25, s39
	s_and_b64 s[44:45], s[8:9], exec
	s_cselect_b32 s31, s39, s5
	s_cselect_b32 s56, s38, s4
	s_add_u32 s42, s42, 0x80080
	s_addc_u32 s43, s43, 0
	s_add_u32 s57, s4, 0x100
	s_addc_u32 s58, s5, 0
	s_mov_b32 s59, -2
	s_waitcnt lgkmcnt(0)
	v_mov_b64_e32 v[0:1], 0
	v_mov_b64_e32 v[2:3], 0
	v_mov_b64_e32 v[4:5], 0
	v_mov_b64_e32 v[6:7], 0
	v_mov_b64_e32 v[16:17], 0
	v_mov_b64_e32 v[18:19], 0
	v_mov_b64_e32 v[20:21], 0
	v_mov_b64_e32 v[22:23], 0
	v_mov_b64_e32 v[32:33], 0
	v_mov_b64_e32 v[34:35], 0
	v_mov_b64_e32 v[36:37], 0
	v_mov_b64_e32 v[38:39], 0
	s_waitcnt vmcnt(0)
	v_mov_b64_e32 v[48:49], 0
	v_mov_b64_e32 v[50:51], 0
	v_mov_b64_e32 v[52:53], 0
	v_mov_b64_e32 v[54:55], 0
	v_mov_b64_e32 v[8:9], 0
	v_mov_b64_e32 v[10:11], 0
	v_mov_b64_e32 v[12:13], 0
	v_mov_b64_e32 v[14:15], 0
	v_mov_b64_e32 v[24:25], 0
	v_mov_b64_e32 v[26:27], 0
	v_mov_b64_e32 v[28:29], 0
	v_mov_b64_e32 v[30:31], 0
	v_mov_b64_e32 v[40:41], 0
	v_mov_b64_e32 v[42:43], 0
	v_mov_b64_e32 v[44:45], 0
	v_mov_b64_e32 v[46:47], 0
	v_mov_b64_e32 v[56:57], 0
	v_mov_b64_e32 v[58:59], 0
	v_mov_b64_e32 v[60:61], 0
	v_mov_b64_e32 v[62:63], 0
	v_mov_b64_e32 v[64:65], 0
	v_mov_b64_e32 v[66:67], 0
	v_mov_b64_e32 v[68:69], 0
	v_mov_b64_e32 v[70:71], 0
	v_mov_b64_e32 v[80:81], 0
	v_mov_b64_e32 v[82:83], 0
	v_mov_b64_e32 v[84:85], 0
	v_mov_b64_e32 v[86:87], 0
	v_mov_b64_e32 v[96:97], 0
	v_mov_b64_e32 v[98:99], 0
	v_mov_b64_e32 v[100:101], 0
	v_mov_b64_e32 v[102:103], 0
	v_mov_b64_e32 v[112:113], 0
	v_mov_b64_e32 v[114:115], 0
	v_mov_b64_e32 v[116:117], 0
	v_mov_b64_e32 v[118:119], 0
	v_mov_b64_e32 v[72:73], 0
	v_mov_b64_e32 v[74:75], 0
	v_mov_b64_e32 v[76:77], 0
	v_mov_b64_e32 v[78:79], 0
	v_mov_b64_e32 v[88:89], 0
	v_mov_b64_e32 v[90:91], 0
	v_mov_b64_e32 v[92:93], 0
	v_mov_b64_e32 v[94:95], 0
	v_mov_b64_e32 v[104:105], 0
	v_mov_b64_e32 v[106:107], 0
	v_mov_b64_e32 v[108:109], 0
	v_mov_b64_e32 v[110:111], 0
	v_mov_b64_e32 v[120:121], 0
	v_mov_b64_e32 v[122:123], 0
	v_mov_b64_e32 v[124:125], 0
	v_mov_b64_e32 v[126:127], 0
	s_cmp_lg_u32 s90, 0
	s_cbranch_scc0 .Lkl_nobar_1
	s_barrier
	s_mov_b32 s90, 0

.LBB0_482:
	s_ashr_i32 s37, s36, 31
	s_lshl_b64 s[12:13], s[36:37], 19
	s_add_u32 s38, s14, s12
	s_addc_u32 s39, s15, s13
	s_and_b64 s[12:13], s[6:7], exec
	s_cselect_b32 s9, s39, s11
	s_cselect_b32 s37, s38, s10
	s_ashr_i32 s35, s34, 31
	s_lshl_b64 s[12:13], s[34:35], 19
	s_add_u32 s40, s20, s12
	s_addc_u32 s41, s22, s13
	s_and_b64 s[12:13], s[6:7], exec
	s_cselect_b32 s35, s41, s5
	s_cselect_b32 s53, s40, s4
	s_add_u32 s10, s10, 0x40080
	s_addc_u32 s11, s11, 0
	s_add_u32 s54, s4, 0x100
	s_addc_u32 s55, s5, 0
	s_mov_b32 s56, -2
	v_mov_b64_e32 v[0:1], 0
	v_mov_b64_e32 v[2:3], 0
	v_mov_b64_e32 v[8:9], 0
	v_mov_b64_e32 v[10:11], 0
	v_mov_b64_e32 v[16:17], 0
	v_mov_b64_e32 v[18:19], 0
	v_mov_b64_e32 v[24:25], 0
	v_mov_b64_e32 v[26:27], 0
	v_mov_b64_e32 v[32:33], 0
	v_mov_b64_e32 v[34:35], 0
	v_mov_b64_e32 v[40:41], 0
	s_waitcnt vmcnt(0)
	v_mov_b64_e32 v[42:43], 0
	v_mov_b64_e32 v[48:49], 0
	v_mov_b64_e32 v[50:51], 0
	v_mov_b64_e32 v[56:57], 0
	v_mov_b64_e32 v[58:59], 0
	v_mov_b64_e32 v[4:5], 0
	v_mov_b64_e32 v[6:7], 0
	v_mov_b64_e32 v[12:13], 0
	v_mov_b64_e32 v[14:15], 0
	v_mov_b64_e32 v[20:21], 0
	v_mov_b64_e32 v[22:23], 0
	v_mov_b64_e32 v[28:29], 0
	v_mov_b64_e32 v[30:31], 0
	v_mov_b64_e32 v[36:37], 0
	v_mov_b64_e32 v[38:39], 0
	v_mov_b64_e32 v[44:45], 0
	v_mov_b64_e32 v[46:47], 0
	v_mov_b64_e32 v[52:53], 0
	v_mov_b64_e32 v[54:55], 0
	v_mov_b64_e32 v[60:61], 0
	v_mov_b64_e32 v[62:63], 0
	v_mov_b64_e32 v[64:65], 0
	v_mov_b64_e32 v[66:67], 0
	v_mov_b64_e32 v[72:73], 0
	v_mov_b64_e32 v[74:75], 0
	v_mov_b64_e32 v[80:81], 0
	v_mov_b64_e32 v[82:83], 0
	v_mov_b64_e32 v[88:89], 0
	v_mov_b64_e32 v[90:91], 0
	v_mov_b64_e32 v[96:97], 0
	v_mov_b64_e32 v[98:99], 0
	v_mov_b64_e32 v[104:105], 0
	v_mov_b64_e32 v[106:107], 0
	v_mov_b64_e32 v[112:113], 0
	v_mov_b64_e32 v[114:115], 0
	v_mov_b64_e32 v[120:121], 0
	v_mov_b64_e32 v[122:123], 0
	v_mov_b64_e32 v[68:69], 0
	v_mov_b64_e32 v[70:71], 0
	v_mov_b64_e32 v[76:77], 0
	v_mov_b64_e32 v[78:79], 0
	v_mov_b64_e32 v[84:85], 0
	v_mov_b64_e32 v[86:87], 0
	v_mov_b64_e32 v[92:93], 0
	v_mov_b64_e32 v[94:95], 0
	v_mov_b64_e32 v[100:101], 0
	v_mov_b64_e32 v[102:103], 0
	v_mov_b64_e32 v[108:109], 0
	v_mov_b64_e32 v[110:111], 0
	v_mov_b64_e32 v[116:117], 0
	v_mov_b64_e32 v[118:119], 0
	v_mov_b64_e32 v[124:125], 0
	v_mov_b64_e32 v[126:127], 0
	s_cmp_lg_u32 s90, 0
	s_cbranch_scc0 .Lkl_nobar_2
	s_barrier
	s_mov_b32 s90, 0

.LBB0_558:
	s_add_u32 s55, s4, 0x100
	s_addc_u32 s56, s5, 0
	s_mov_b32 s57, -2
	s_waitcnt lgkmcnt(0)
	v_mov_b64_e32 v[0:1], 0
	v_mov_b64_e32 v[2:3], 0
	v_mov_b64_e32 v[4:5], 0
	v_mov_b64_e32 v[6:7], 0
	v_mov_b64_e32 v[16:17], 0
	v_mov_b64_e32 v[18:19], 0
	v_mov_b64_e32 v[20:21], 0
	v_mov_b64_e32 v[22:23], 0
	v_mov_b64_e32 v[32:33], 0
	v_mov_b64_e32 v[34:35], 0
	v_mov_b64_e32 v[36:37], 0
	v_mov_b64_e32 v[38:39], 0
	s_waitcnt vmcnt(0)
	v_mov_b64_e32 v[48:49], 0
	v_mov_b64_e32 v[50:51], 0
	v_mov_b64_e32 v[52:53], 0
	v_mov_b64_e32 v[54:55], 0
	v_mov_b64_e32 v[8:9], 0
	v_mov_b64_e32 v[10:11], 0
	v_mov_b64_e32 v[12:13], 0
	v_mov_b64_e32 v[14:15], 0
	v_mov_b64_e32 v[24:25], 0
	v_mov_b64_e32 v[26:27], 0
	v_mov_b64_e32 v[28:29], 0
	v_mov_b64_e32 v[30:31], 0
	v_mov_b64_e32 v[40:41], 0
	v_mov_b64_e32 v[42:43], 0
	v_mov_b64_e32 v[44:45], 0
	v_mov_b64_e32 v[46:47], 0
	v_mov_b64_e32 v[56:57], 0
	v_mov_b64_e32 v[58:59], 0
	v_mov_b64_e32 v[60:61], 0
	v_mov_b64_e32 v[62:63], 0
	v_mov_b64_e32 v[64:65], 0
	v_mov_b64_e32 v[66:67], 0
	v_mov_b64_e32 v[68:69], 0
	v_mov_b64_e32 v[70:71], 0
	v_mov_b64_e32 v[80:81], 0
	v_mov_b64_e32 v[82:83], 0
	v_mov_b64_e32 v[84:85], 0
	v_mov_b64_e32 v[86:87], 0
	v_mov_b64_e32 v[96:97], 0
	v_mov_b64_e32 v[98:99], 0
	v_mov_b64_e32 v[100:101], 0
	v_mov_b64_e32 v[102:103], 0
	v_mov_b64_e32 v[112:113], 0
	v_mov_b64_e32 v[114:115], 0
	v_mov_b64_e32 v[116:117], 0
	v_mov_b64_e32 v[118:119], 0
	v_mov_b64_e32 v[72:73], 0
	v_mov_b64_e32 v[74:75], 0
	v_mov_b64_e32 v[76:77], 0
	v_mov_b64_e32 v[78:79], 0
	v_mov_b64_e32 v[88:89], 0
	v_mov_b64_e32 v[90:91], 0
	v_mov_b64_e32 v[92:93], 0
	v_mov_b64_e32 v[94:95], 0
	v_mov_b64_e32 v[104:105], 0
	v_mov_b64_e32 v[106:107], 0
	v_mov_b64_e32 v[108:109], 0
	v_mov_b64_e32 v[110:111], 0
	v_mov_b64_e32 v[120:121], 0
	v_mov_b64_e32 v[122:123], 0
	v_mov_b64_e32 v[124:125], 0
	v_mov_b64_e32 v[126:127], 0
	s_cmp_lg_u32 s90, 0
	s_cbranch_scc0 .Lkl_nobar_3
	s_barrier
	s_mov_b32 s90, 0

.LBB0_642:
	s_ashr_i32 s41, s40, 31
	s_lshl_b64 s[42:43], s[40:41], 19
	s_add_u32 s42, s14, s42
	s_addc_u32 s43, s15, s43
	s_and_b64 s[44:45], s[10:11], exec
	s_cselect_b32 s13, s43, s23
	s_cselect_b32 s17, s42, s22
	s_ashr_i32 s39, s38, 31
	s_lshl_b64 s[44:45], s[38:39], 19
	s_add_u32 s44, s20, s44
	s_addc_u32 s45, s25, s45
	s_and_b64 s[46:47], s[10:11], exec
	s_cselect_b32 s33, s45, s5
	s_cselect_b32 s39, s44, s4
	s_add_u32 s22, s22, 0x40080
	s_addc_u32 s23, s23, 0
	s_add_u32 s41, s4, 0x100
	s_addc_u32 s62, s5, 0
	s_mov_b32 s63, -2
	v_mov_b64_e32 v[0:1], 0
	v_mov_b64_e32 v[2:3], 0
	v_mov_b64_e32 v[4:5], 0
	v_mov_b64_e32 v[6:7], 0
	s_waitcnt vmcnt(0)
	v_mov_b64_e32 v[16:17], 0
	v_mov_b64_e32 v[18:19], 0
	v_mov_b64_e32 v[20:21], 0
	v_mov_b64_e32 v[22:23], 0
	v_mov_b64_e32 v[32:33], 0
	v_mov_b64_e32 v[34:35], 0
	v_mov_b64_e32 v[36:37], 0
	v_mov_b64_e32 v[38:39], 0
	s_waitcnt vmcnt(0)
	v_mov_b64_e32 v[48:49], 0
	v_mov_b64_e32 v[50:51], 0
	v_mov_b64_e32 v[52:53], 0
	v_mov_b64_e32 v[54:55], 0
	v_mov_b64_e32 v[8:9], 0
	v_mov_b64_e32 v[10:11], 0
	v_mov_b64_e32 v[12:13], 0
	v_mov_b64_e32 v[14:15], 0
	v_mov_b64_e32 v[24:25], 0
	v_mov_b64_e32 v[26:27], 0
	v_mov_b64_e32 v[28:29], 0
	v_mov_b64_e32 v[30:31], 0
	v_mov_b64_e32 v[40:41], 0
	v_mov_b64_e32 v[42:43], 0
	v_mov_b64_e32 v[44:45], 0
	v_mov_b64_e32 v[46:47], 0
	v_mov_b64_e32 v[56:57], 0
	v_mov_b64_e32 v[58:59], 0
	v_mov_b64_e32 v[60:61], 0
	v_mov_b64_e32 v[62:63], 0
	v_mov_b64_e32 v[64:65], 0
	v_mov_b64_e32 v[66:67], 0
	v_mov_b64_e32 v[68:69], 0
	v_mov_b64_e32 v[70:71], 0
	v_mov_b64_e32 v[80:81], 0
	v_mov_b64_e32 v[82:83], 0
	v_mov_b64_e32 v[84:85], 0
	v_mov_b64_e32 v[86:87], 0
	v_mov_b64_e32 v[96:97], 0
	v_mov_b64_e32 v[98:99], 0
	v_mov_b64_e32 v[100:101], 0
	v_mov_b64_e32 v[102:103], 0
	v_mov_b64_e32 v[112:113], 0
	v_mov_b64_e32 v[114:115], 0
	v_mov_b64_e32 v[116:117], 0
	v_mov_b64_e32 v[118:119], 0
	v_mov_b64_e32 v[72:73], 0
	v_mov_b64_e32 v[74:75], 0
	v_mov_b64_e32 v[76:77], 0
	v_mov_b64_e32 v[78:79], 0
	v_mov_b64_e32 v[88:89], 0
	v_mov_b64_e32 v[90:91], 0
	v_mov_b64_e32 v[92:93], 0
	v_mov_b64_e32 v[94:95], 0
	v_mov_b64_e32 v[104:105], 0
	v_mov_b64_e32 v[106:107], 0
	v_mov_b64_e32 v[108:109], 0
	v_mov_b64_e32 v[110:111], 0
	v_mov_b64_e32 v[120:121], 0
	v_mov_b64_e32 v[122:123], 0
	v_mov_b64_e32 v[124:125], 0
	v_mov_b64_e32 v[126:127], 0
	s_cmp_lg_u32 s90, 0
	s_cbranch_scc0 .Lkl_nobar_4
	s_barrier
	s_mov_b32 s90, 0

.LBB0_965:
	s_ashr_i32 s35, s34, 31
	s_lshl_b64 s[36:37], s[34:35], 19
	s_add_u32 s36, s14, s36
	s_addc_u32 s37, s15, s37
	s_and_b64 s[38:39], s[8:9], exec
	s_cselect_b32 s35, s37, s23
	s_cselect_b32 s41, s36, s22
	s_ashr_i32 s31, s30, 31
	s_lshl_b64 s[38:39], s[30:31], 19
	s_add_u32 s38, s20, s38
	s_addc_u32 s39, s44, s39
	s_and_b64 s[42:43], s[8:9], exec
	s_cselect_b32 s31, s39, s5
	s_cselect_b32 s55, s38, s4
	s_add_u32 s22, s22, 0x40080
	s_addc_u32 s23, s23, 0
	s_add_u32 s56, s4, 0x100
	s_addc_u32 s57, s5, 0
	s_mov_b32 s58, -2
	s_waitcnt lgkmcnt(0)
	v_mov_b64_e32 v[0:1], 0
	v_mov_b64_e32 v[2:3], 0
	v_mov_b64_e32 v[4:5], 0
	v_mov_b64_e32 v[6:7], 0
	v_mov_b64_e32 v[16:17], 0
	v_mov_b64_e32 v[18:19], 0
	v_mov_b64_e32 v[20:21], 0
	v_mov_b64_e32 v[22:23], 0
	v_mov_b64_e32 v[32:33], 0
	v_mov_b64_e32 v[34:35], 0
	v_mov_b64_e32 v[36:37], 0
	v_mov_b64_e32 v[38:39], 0
	v_mov_b64_e32 v[48:49], 0
	v_mov_b64_e32 v[50:51], 0
	v_mov_b64_e32 v[52:53], 0
	v_mov_b64_e32 v[54:55], 0
	v_mov_b64_e32 v[8:9], 0
	v_mov_b64_e32 v[10:11], 0
	v_mov_b64_e32 v[12:13], 0
	v_mov_b64_e32 v[14:15], 0
	v_mov_b64_e32 v[24:25], 0
	v_mov_b64_e32 v[26:27], 0
	v_mov_b64_e32 v[28:29], 0
	v_mov_b64_e32 v[30:31], 0
	v_mov_b64_e32 v[40:41], 0
	v_mov_b64_e32 v[42:43], 0
	v_mov_b64_e32 v[44:45], 0
	v_mov_b64_e32 v[46:47], 0
	v_mov_b64_e32 v[56:57], 0
	v_mov_b64_e32 v[58:59], 0
	v_mov_b64_e32 v[60:61], 0
	v_mov_b64_e32 v[62:63], 0
	v_mov_b64_e32 v[64:65], 0
	v_mov_b64_e32 v[66:67], 0
	v_mov_b64_e32 v[68:69], 0
	v_mov_b64_e32 v[70:71], 0
	v_mov_b64_e32 v[80:81], 0
	v_mov_b64_e32 v[82:83], 0
	v_mov_b64_e32 v[84:85], 0
	v_mov_b64_e32 v[86:87], 0
	v_mov_b64_e32 v[96:97], 0
	v_mov_b64_e32 v[98:99], 0
	v_mov_b64_e32 v[100:101], 0
	v_mov_b64_e32 v[102:103], 0
	v_mov_b64_e32 v[112:113], 0
	v_mov_b64_e32 v[114:115], 0
	v_mov_b64_e32 v[116:117], 0
	v_mov_b64_e32 v[118:119], 0
	v_mov_b64_e32 v[72:73], 0
	v_mov_b64_e32 v[74:75], 0
	v_mov_b64_e32 v[76:77], 0
	v_mov_b64_e32 v[78:79], 0
	v_mov_b64_e32 v[88:89], 0
	v_mov_b64_e32 v[90:91], 0
	v_mov_b64_e32 v[92:93], 0
	v_mov_b64_e32 v[94:95], 0
	v_mov_b64_e32 v[104:105], 0
	v_mov_b64_e32 v[106:107], 0
	v_mov_b64_e32 v[108:109], 0
	v_mov_b64_e32 v[110:111], 0
	v_mov_b64_e32 v[120:121], 0
	v_mov_b64_e32 v[122:123], 0
	v_mov_b64_e32 v[124:125], 0
	v_mov_b64_e32 v[126:127], 0
	s_cmp_lg_u32 s90, 0
	s_cbranch_scc0 .Lkl_nobar_5
	s_barrier
	s_mov_b32 s90, 0

.LBB0_1047:
	s_ashr_i32 s31, s30, 31
	s_lshl_b64 s[12:13], s[30:31], 19
	s_add_u32 s34, s14, s12
	s_addc_u32 s35, s15, s13
	s_and_b64 s[12:13], s[6:7], exec
	s_cselect_b32 s9, s35, s11
	s_cselect_b32 s31, s34, s10
	s_ashr_i32 s29, s28, 31
	s_lshl_b64 s[12:13], s[28:29], 19
	s_add_u32 s36, s20, s12
	s_addc_u32 s37, s38, s13
	s_and_b64 s[12:13], s[6:7], exec
	s_cselect_b32 s29, s37, s5
	s_cselect_b32 s52, s36, s4
	s_add_u32 s10, s10, 0x40080
	s_addc_u32 s11, s11, 0
	s_add_u32 s53, s4, 0x100
	s_addc_u32 s54, s5, 0
	s_mov_b32 s55, -2
	v_mov_b64_e32 v[0:1], 0
	v_mov_b64_e32 v[2:3], 0
	v_mov_b64_e32 v[8:9], 0
	v_mov_b64_e32 v[10:11], 0
	v_mov_b64_e32 v[16:17], 0
	v_mov_b64_e32 v[18:19], 0
	v_mov_b64_e32 v[24:25], 0
	v_mov_b64_e32 v[26:27], 0
	v_mov_b64_e32 v[32:33], 0
	v_mov_b64_e32 v[34:35], 0
	v_mov_b64_e32 v[40:41], 0
	v_mov_b64_e32 v[42:43], 0
	v_mov_b64_e32 v[48:49], 0
	v_mov_b64_e32 v[50:51], 0
	v_mov_b64_e32 v[56:57], 0
	v_mov_b64_e32 v[58:59], 0
	v_mov_b64_e32 v[4:5], 0
	v_mov_b64_e32 v[6:7], 0
	v_mov_b64_e32 v[12:13], 0
	v_mov_b64_e32 v[14:15], 0
	v_mov_b64_e32 v[20:21], 0
	v_mov_b64_e32 v[22:23], 0
	v_mov_b64_e32 v[28:29], 0
	v_mov_b64_e32 v[30:31], 0
	v_mov_b64_e32 v[36:37], 0
	v_mov_b64_e32 v[38:39], 0
	v_mov_b64_e32 v[44:45], 0
	v_mov_b64_e32 v[46:47], 0
	v_mov_b64_e32 v[52:53], 0
	v_mov_b64_e32 v[54:55], 0
	v_mov_b64_e32 v[60:61], 0
	v_mov_b64_e32 v[62:63], 0
	v_mov_b64_e32 v[64:65], 0
	v_mov_b64_e32 v[66:67], 0
	v_mov_b64_e32 v[72:73], 0
	v_mov_b64_e32 v[74:75], 0
	v_mov_b64_e32 v[80:81], 0
	v_mov_b64_e32 v[82:83], 0
	v_mov_b64_e32 v[88:89], 0
	v_mov_b64_e32 v[90:91], 0
	v_mov_b64_e32 v[96:97], 0
	v_mov_b64_e32 v[98:99], 0
	v_mov_b64_e32 v[104:105], 0
	v_mov_b64_e32 v[106:107], 0
	v_mov_b64_e32 v[112:113], 0
	v_mov_b64_e32 v[114:115], 0
	v_mov_b64_e32 v[120:121], 0
	v_mov_b64_e32 v[122:123], 0
	v_mov_b64_e32 v[68:69], 0
	v_mov_b64_e32 v[70:71], 0
	v_mov_b64_e32 v[76:77], 0
	v_mov_b64_e32 v[78:79], 0
	v_mov_b64_e32 v[84:85], 0
	v_mov_b64_e32 v[86:87], 0
	v_mov_b64_e32 v[92:93], 0
	v_mov_b64_e32 v[94:95], 0
	v_mov_b64_e32 v[100:101], 0
	v_mov_b64_e32 v[102:103], 0
	v_mov_b64_e32 v[108:109], 0
	v_mov_b64_e32 v[110:111], 0
	v_mov_b64_e32 v[116:117], 0
	v_mov_b64_e32 v[118:119], 0
	v_mov_b64_e32 v[124:125], 0
	v_mov_b64_e32 v[126:127], 0
	s_cmp_lg_u32 s90, 0
	s_cbranch_scc0 .Lkl_nobar_6
	s_barrier
	s_mov_b32 s90, 0

.LBB0_1123:
	s_add_u32 s54, s34, 0x100
	s_addc_u32 s55, s35, 0
	s_mov_b32 s56, -2
	s_waitcnt lgkmcnt(0)
	v_mov_b64_e32 v[0:1], 0
	v_mov_b64_e32 v[2:3], 0
	v_mov_b64_e32 v[4:5], 0
	v_mov_b64_e32 v[6:7], 0
	v_mov_b64_e32 v[16:17], 0
	v_mov_b64_e32 v[18:19], 0
	v_mov_b64_e32 v[20:21], 0
	v_mov_b64_e32 v[22:23], 0
	v_mov_b64_e32 v[32:33], 0
	v_mov_b64_e32 v[34:35], 0
	v_mov_b64_e32 v[36:37], 0
	v_mov_b64_e32 v[38:39], 0
	v_mov_b64_e32 v[48:49], 0
	v_mov_b64_e32 v[50:51], 0
	v_mov_b64_e32 v[52:53], 0
	v_mov_b64_e32 v[54:55], 0
	v_mov_b64_e32 v[8:9], 0
	v_mov_b64_e32 v[10:11], 0
	v_mov_b64_e32 v[12:13], 0
	v_mov_b64_e32 v[14:15], 0
	v_mov_b64_e32 v[24:25], 0
	v_mov_b64_e32 v[26:27], 0
	v_mov_b64_e32 v[28:29], 0
	v_mov_b64_e32 v[30:31], 0
	v_mov_b64_e32 v[40:41], 0
	v_mov_b64_e32 v[42:43], 0
	v_mov_b64_e32 v[44:45], 0
	v_mov_b64_e32 v[46:47], 0
	v_mov_b64_e32 v[56:57], 0
	v_mov_b64_e32 v[58:59], 0
	v_mov_b64_e32 v[60:61], 0
	v_mov_b64_e32 v[62:63], 0
	v_mov_b64_e32 v[64:65], 0
	v_mov_b64_e32 v[66:67], 0
	v_mov_b64_e32 v[68:69], 0
	v_mov_b64_e32 v[70:71], 0
	v_mov_b64_e32 v[80:81], 0
	v_mov_b64_e32 v[82:83], 0
	v_mov_b64_e32 v[84:85], 0
	v_mov_b64_e32 v[86:87], 0
	v_mov_b64_e32 v[96:97], 0
	v_mov_b64_e32 v[98:99], 0
	v_mov_b64_e32 v[100:101], 0
	v_mov_b64_e32 v[102:103], 0
	v_mov_b64_e32 v[112:113], 0
	v_mov_b64_e32 v[114:115], 0
	v_mov_b64_e32 v[116:117], 0
	v_mov_b64_e32 v[118:119], 0
	v_mov_b64_e32 v[72:73], 0
	v_mov_b64_e32 v[74:75], 0
	v_mov_b64_e32 v[76:77], 0
	v_mov_b64_e32 v[78:79], 0
	v_mov_b64_e32 v[88:89], 0
	v_mov_b64_e32 v[90:91], 0
	v_mov_b64_e32 v[92:93], 0
	v_mov_b64_e32 v[94:95], 0
	v_mov_b64_e32 v[104:105], 0
	v_mov_b64_e32 v[106:107], 0
	v_mov_b64_e32 v[108:109], 0
	v_mov_b64_e32 v[110:111], 0
	v_mov_b64_e32 v[120:121], 0
	v_mov_b64_e32 v[122:123], 0
	v_mov_b64_e32 v[124:125], 0
	v_mov_b64_e32 v[126:127], 0
	s_cmp_lg_u32 s90, 0
	s_cbranch_scc0 .Lkl_nobar_7
	s_barrier
	s_mov_b32 s90, 0
